# grid barrier: L1 invalidate issued with the arrival atomic (overlaps the round trip and the spin) instead of after the release
# speedup vs baseline: 1.0827x; 1.0114x over previous
.Lcgx_267:
	s_or_b64 exec, exec, s[12:13]
	buffer_inv sc1
	v_cvt_f32_u32_e32 v4, v2
	s_waitcnt vmcnt(0)
	v_readfirstlane_b32 s3, v3
	v_sub_u32_e32 v3, 0, v2
	v_rcp_iflag_f32_e32 v4, v4
	v_add_u32_e32 v5, s3, v1
	v_mul_f32_e32 v4, 0x4f7ffffe, v4
	v_cvt_u32_f32_e32 v4, v4
	v_mul_lo_u32 v1, v3, v4
	v_mul_hi_u32 v1, v4, v1
	v_add_u32_e32 v1, v4, v1
	v_mul_hi_u32 v1, v5, v1
	v_mul_lo_u32 v3, v1, v2
	v_sub_u32_e32 v3, v5, v3
	v_add_u32_e32 v4, 1, v1
	v_cmp_ge_u32_e32 vcc, v3, v2
	s_nop 1
	v_cndmask_b32_e32 v1, v1, v4, vcc
	v_sub_u32_e32 v4, v3, v2
	v_cndmask_b32_e32 v3, v3, v4, vcc
	v_add_u32_e32 v4, 1, v1
	v_cmp_ge_u32_e32 vcc, v3, v2
	v_add_u32_e32 v3, 1, v5
	s_nop 0
	v_cndmask_b32_e32 v1, v1, v4, vcc
	v_mul_lo_u32 v4, v2, v1
	v_add_u32_e32 v2, v4, v2
	v_cmp_ne_u32_e32 vcc, v3, v2
	s_and_saveexec_b64 s[10:11], vcc
	s_xor_b64 s[10:11], exec, s[10:11]
	s_cbranch_execz .Lcgx_281
	s_waitcnt lgkmcnt(0)
	v_mov_b32_e32 v0, 0x7500
	global_load_dword v0, v0, s[6:7] sc1
	s_add_u32 s16, s6, 0x7500
	s_addc_u32 s17, s7, 0
	s_waitcnt vmcnt(0)
	v_cmp_eq_u32_e32 vcc, v0, v1
	s_and_saveexec_b64 s[12:13], vcc
	s_cbranch_execz .Lcgx_280
	s_add_u32 s14, s6, 0x4200
	s_addc_u32 s15, s7, 0
	s_mov_b32 s3, 1
	s_mov_b64 s[18:19], 0
	v_mov_b32_e32 v0, 0
	s_branch .Lcgx_271

.Lcgx_280:
	s_or_b64 exec, exec, s[12:13]
	s_waitcnt vmcnt(0)
	s_waitcnt vmcnt(0)

.Lcgx_298:
	s_or_b64 exec, exec, s[6:7]
	s_mov_b64 s[6:7], exec
	v_mbcnt_lo_u32_b32 v0, s6, 0
	v_mbcnt_hi_u32_b32 v0, s7, v0
	v_cmp_eq_u32_e32 vcc, 0, v0
	s_waitcnt vmcnt(0)
	s_and_saveexec_b64 s[10:11], vcc
	s_cbranch_execz .Lcgx_300
	s_bcnt1_i32_b64 s3, s[6:7]
	v_mov_b32_e32 v0, 0x2000
	v_mov_b32_e32 v1, s3
	global_atomic_add v0, v1, s[8:9] offset:1024
